# v07: + skip WO->N1 grid barrier for group 0, drop final grid barrier, replace cg grid.sync by custom barrier, batch the rpb max-reduction loads in the mixer prologue
# speedup vs baseline: 1.0166x; 1.0166x over previous
.LBB0_252:
	v_lshrrev_b32_e32 v1, 20, v0
	v_lshrrev_b32_e32 v0, 10, v0
	v_or_b32_e32 v0, v0, v1
	s_movk_i32 s6, 0x3ff
	v_and_or_b32 v0, v0, s6, v246
	v_cmp_eq_u32_e32 vcc, 0, v0
	s_barrier
	s_barrier
	s_and_saveexec_b64 s[6:7], vcc
	s_branch .LBB0_262

.LBB0_268:
	v_readlane_b32 s2, v254, 40
	v_readlane_b32 s3, v254, 41
	s_and_b64 s[2:3], s[2:3], s[6:7]
	s_andn2_b64 vcc, exec, s[2:3]
	s_cbranch_vccz .Lctxfix_do
	v_readlane_b32 s98, v254, 40
	v_readlane_b32 s99, v254, 41
	s_nop 3
	s_andn2_b64 s[98:99], s[6:7], s[98:99]
	s_cmp_lg_u64 s[98:99], 0
	s_cbranch_scc0 .LBB0_325
	s_mov_b64 s[2:3], exec
	s_branch .LBB0_272
.Lctxfix_do:
	v_mov_b32_e32 v16, v246
	v_readlane_b32 s2, v252, 0
	v_ashrrev_i32_e32 v0, 6, v16
	s_nop 0
	v_add_u32_e32 v12, s2, v0
	s_movk_i32 s2, 0x800
	v_cmp_gt_i32_e32 vcc, s2, v12
	s_and_saveexec_b64 s[2:3], vcc
	s_cbranch_execz .LBB0_272
	v_lshlrev_b32_e32 v0, 4, v16
	s_add_u32 s8, s88, 0x135000
	v_and_b32_e32 v112, 0x3f0, v0
	s_addc_u32 s9, s89, 0
	v_or_b32_e32 v2, 0x400, v112
	v_mov_b32_e32 v3, v113
	v_lshl_add_u64 v[4:5], s[8:9], 0, v[2:3]
	v_or_b32_e32 v2, 0x800, v112
	v_lshl_add_u64 v[0:1], s[8:9], 0, v[112:113]
	v_lshl_add_u64 v[8:9], s[8:9], 0, v[2:3]
	global_load_dwordx4 v[0:3], v[0:1], off
	s_nop 0
	global_load_dwordx4 v[4:7], v[4:5], off
	s_nop 0
	global_load_dwordx4 v[8:11], v[8:9], off
	v_ashrrev_i32_e32 v13, 31, v12
	v_lshlrev_b64 v[18:19], 12, v[12:13]
	v_and_b32_e32 v13, 63, v16
	v_or_b32_e32 v112, 0xc00, v112
	v_lshl_or_b32 v18, v13, 4, v18
	v_lshl_add_u64 v[14:15], s[8:9], 0, v[112:113]
	v_lshl_add_u64 v[16:17], s[88:89], 0, v[18:19]
	s_mov_b64 s[8:9], 0x1a800000
	v_lshl_add_u64 v[16:17], v[16:17], 0, s[8:9]
	s_mov_b64 s[8:9], 0

.LBB0_276:
	v_readlane_b32 s8, v252, 3
	v_readlane_b32 s9, v252, 4
	v_readlane_b32 s10, v254, 7
	s_waitcnt lgkmcnt(0)
	s_nop 2
	global_load_dword v0, v113, s[8:9] sc1
	global_load_dword v1, v113, s[8:9] offset:256 sc1
	global_load_dword v2, v113, s[8:9] offset:512 sc1
	global_load_dword v3, v113, s[8:9] offset:768 sc1
	global_load_dword v4, v113, s[8:9] offset:1024 sc1
	global_load_dword v5, v113, s[8:9] offset:1280 sc1
	global_load_dword v6, v113, s[8:9] offset:1536 sc1
	global_load_dword v7, v113, s[8:9] offset:1792 sc1
	global_load_dword v8, v113, s[8:9] offset:2048 sc1
	global_load_dword v9, v113, s[8:9] offset:2304 sc1
	global_load_dword v10, v113, s[8:9] offset:2560 sc1
	global_load_dword v11, v113, s[8:9] offset:2816 sc1
	global_load_dword v12, v113, s[8:9] offset:3072 sc1
	global_load_dword v13, v113, s[8:9] offset:3328 sc1
	global_load_dword v14, v113, s[8:9] offset:3584 sc1
	global_load_dword v15, v113, s[8:9] offset:3840 sc1
	s_mov_b64 s[8:9], -1
	s_waitcnt vmcnt(0)
	v_add_u32_e32 v16, v1, v0
	v_add_u32_e32 v16, v16, v2
	v_add_u32_e32 v16, v16, v3
	v_add_u32_e32 v16, v16, v4
	v_add_u32_e32 v16, v16, v5
	v_add_u32_e32 v16, v16, v6
	v_add_u32_e32 v16, v16, v7
	v_add_u32_e32 v16, v16, v8
	v_add_u32_e32 v16, v16, v9
	v_add_u32_e32 v16, v16, v10
	v_add_u32_e32 v16, v16, v11
	v_add_u32_e32 v16, v16, v12
	v_add_u32_e32 v16, v16, v13
	v_add_u32_e32 v16, v16, v14
	v_add_u32_e32 v16, v16, v15
	v_cmp_eq_u32_e32 vcc, s10, v16
	s_mov_b64 s[10:11], -1
	s_cbranch_vccnz .LBB0_275
	s_and_b32 s8, s14, 0xff
	s_cmp_eq_u32 s8, 0
	s_mov_b64 s[8:9], -1
	s_mov_b64 s[12:13], -1
	s_sleep 1
	s_cbranch_scc1 .LBB0_280
	s_and_b64 vcc, exec, s[12:13]
	s_cbranch_vccz .LBB0_275

.LBB0_999:
	global_load_dword v9, v[6:7], off
	v_max_f32_e32 v8, v8, v8
	v_add_u32_e32 v3, 64, v3
	v_max_f32_e32 v1, v1, v1
	v_cmp_lt_u32_e32 vcc, 31, v3
	v_lshl_add_u64 v[6:7], v[6:7], 0, s[6:7]
	s_or_b64 s[2:3], vcc, s[2:3]
	s_waitcnt vmcnt(0)
	v_max_f32_e64 v9, |v9|, |v9|
	v_max_f32_e32 v8, v8, v9
	global_load_dword v9, v[4:5], off
	v_lshl_add_u64 v[4:5], v[4:5], 0, s[6:7]
	s_waitcnt vmcnt(0)
	v_max_f32_e64 v9, |v9|, |v9|
	v_max_f32_e32 v1, v1, v9
	s_andn2_b64 exec, exec, s[2:3]
	s_cbranch_execnz .LBB0_999
	s_or_b64 exec, exec, s[2:3]
	s_load_dwordx4 s[44:47], s[84:85], 0xa0
	s_load_dwordx2 s[10:11], s[84:85], 0xb0
	v_readlane_b32 s2, v254, 62
	v_sub_u32_e32 v3, 0xe87, v2
	v_lshrrev_b32_e32 v3, 6, v3
	v_or_b32_e32 v112, s2, v2
	v_lshlrev_b64 v[4:5], 2, v[112:113]
	s_waitcnt lgkmcnt(0)
	v_lshl_add_u64 v[6:7], s[44:45], 0, v[4:5]
	v_lshl_add_u64 v[4:5], s[46:47], 0, v[4:5]
	global_load_dword v7, v[6:7], off
	v_add_u32_e32 v10, 1, v3
	global_load_dword v6, v[4:5], off
	v_or_b32_e32 v3, 64, v2
	v_readlane_b32 s3, v254, 63
	s_mov_b32 s12, 2
	v_and_b32_e32 v9, 62, v10
	v_mov_b32_e32 v12, 0
	s_mov_b64 s[8:9], 0
	v_mov_b64_e32 v[4:5], v[2:3]
	v_mov_b32_e32 v3, 0
	v_readlane_b32 s13, v255, 10
	v_readlane_b32 s14, v255, 11
	s_nop 1
	v_add_u32_e32 v112, s13, v2
	v_lshl_add_u64 v[12:13], v[112:113], 2, s[10:11]
	s_mov_b64 s[98:99], 0x1000
	v_mov_b32_e32 v4, 0
	global_load_dword v16, v[12:13], off
	global_load_dword v17, v[12:13], off offset:256
	global_load_dword v18, v[12:13], off offset:512
	global_load_dword v19, v[12:13], off offset:768
	global_load_dword v20, v[12:13], off offset:1024
	global_load_dword v21, v[12:13], off offset:1280
	global_load_dword v22, v[12:13], off offset:1536
	global_load_dword v23, v[12:13], off offset:1792
	global_load_dword v24, v[12:13], off offset:2048
	global_load_dword v25, v[12:13], off offset:2304
	global_load_dword v26, v[12:13], off offset:2560
	global_load_dword v27, v[12:13], off offset:2816
	global_load_dword v28, v[12:13], off offset:3072
	global_load_dword v29, v[12:13], off offset:3328
	global_load_dword v30, v[12:13], off offset:3584
	global_load_dword v31, v[12:13], off offset:3840
	v_lshl_add_u64 v[12:13], v[12:13], 0, s[98:99]
	s_waitcnt vmcnt(0)
	v_max_f32_e64 v16, |v16|, |v16|
	v_max_f32_e32 v4, v4, v16
	v_max_f32_e64 v17, |v17|, |v17|
	v_max_f32_e32 v4, v4, v17
	v_max_f32_e64 v18, |v18|, |v18|
	v_max_f32_e32 v4, v4, v18
	v_max_f32_e64 v19, |v19|, |v19|
	v_max_f32_e32 v4, v4, v19
	v_max_f32_e64 v20, |v20|, |v20|
	v_max_f32_e32 v4, v4, v20
	v_max_f32_e64 v21, |v21|, |v21|
	v_max_f32_e32 v4, v4, v21
	v_max_f32_e64 v22, |v22|, |v22|
	v_max_f32_e32 v4, v4, v22
	v_max_f32_e64 v23, |v23|, |v23|
	v_max_f32_e32 v4, v4, v23
	v_max_f32_e64 v24, |v24|, |v24|
	v_max_f32_e32 v4, v4, v24
	v_max_f32_e64 v25, |v25|, |v25|
	v_max_f32_e32 v4, v4, v25
	v_max_f32_e64 v26, |v26|, |v26|
	v_max_f32_e32 v4, v4, v26
	v_max_f32_e64 v27, |v27|, |v27|
	v_max_f32_e32 v4, v4, v27
	v_max_f32_e64 v28, |v28|, |v28|
	v_max_f32_e32 v4, v4, v28
	v_max_f32_e64 v29, |v29|, |v29|
	v_max_f32_e32 v4, v4, v29
	v_max_f32_e64 v30, |v30|, |v30|
	v_max_f32_e32 v4, v4, v30
	v_max_f32_e64 v31, |v31|, |v31|
	v_max_f32_e32 v4, v4, v31
	global_load_dword v16, v[12:13], off
	global_load_dword v17, v[12:13], off offset:256
	global_load_dword v18, v[12:13], off offset:512
	global_load_dword v19, v[12:13], off offset:768
	global_load_dword v20, v[12:13], off offset:1024
	global_load_dword v21, v[12:13], off offset:1280
	global_load_dword v22, v[12:13], off offset:1536
	global_load_dword v23, v[12:13], off offset:1792
	global_load_dword v24, v[12:13], off offset:2048
	global_load_dword v25, v[12:13], off offset:2304
	global_load_dword v26, v[12:13], off offset:2560
	global_load_dword v27, v[12:13], off offset:2816
	global_load_dword v28, v[12:13], off offset:3072
	global_load_dword v29, v[12:13], off offset:3328
	global_load_dword v30, v[12:13], off offset:3584
	global_load_dword v31, v[12:13], off offset:3840
	v_lshl_add_u64 v[12:13], v[12:13], 0, s[98:99]
	s_waitcnt vmcnt(0)
	v_max_f32_e64 v16, |v16|, |v16|
	v_max_f32_e32 v4, v4, v16
	v_max_f32_e64 v17, |v17|, |v17|
	v_max_f32_e32 v4, v4, v17
	v_max_f32_e64 v18, |v18|, |v18|
	v_max_f32_e32 v4, v4, v18
	v_max_f32_e64 v19, |v19|, |v19|
	v_max_f32_e32 v4, v4, v19
	v_max_f32_e64 v20, |v20|, |v20|
	v_max_f32_e32 v4, v4, v20
	v_max_f32_e64 v21, |v21|, |v21|
	v_max_f32_e32 v4, v4, v21
	v_max_f32_e64 v22, |v22|, |v22|
	v_max_f32_e32 v4, v4, v22
	v_max_f32_e64 v23, |v23|, |v23|
	v_max_f32_e32 v4, v4, v23
	v_max_f32_e64 v24, |v24|, |v24|
	v_max_f32_e32 v4, v4, v24
	v_max_f32_e64 v25, |v25|, |v25|
	v_max_f32_e32 v4, v4, v25
	v_max_f32_e64 v26, |v26|, |v26|
	v_max_f32_e32 v4, v4, v26
	v_max_f32_e64 v27, |v27|, |v27|
	v_max_f32_e32 v4, v4, v27
	v_max_f32_e64 v28, |v28|, |v28|
	v_max_f32_e32 v4, v4, v28
	v_max_f32_e64 v29, |v29|, |v29|
	v_max_f32_e32 v4, v4, v29
	v_max_f32_e64 v30, |v30|, |v30|
	v_max_f32_e32 v4, v4, v30
	v_max_f32_e64 v31, |v31|, |v31|
	v_max_f32_e32 v4, v4, v31
	global_load_dword v16, v[12:13], off
	global_load_dword v17, v[12:13], off offset:256
	global_load_dword v18, v[12:13], off offset:512
	global_load_dword v19, v[12:13], off offset:768
	global_load_dword v20, v[12:13], off offset:1024
	global_load_dword v21, v[12:13], off offset:1280
	global_load_dword v22, v[12:13], off offset:1536
	global_load_dword v23, v[12:13], off offset:1792
	global_load_dword v24, v[12:13], off offset:2048
	global_load_dword v25, v[12:13], off offset:2304
	global_load_dword v26, v[12:13], off offset:2560
	global_load_dword v27, v[12:13], off offset:2816
	global_load_dword v28, v[12:13], off offset:3072
	global_load_dword v29, v[12:13], off offset:3328
	global_load_dword v30, v[12:13], off offset:3584
	global_load_dword v31, v[12:13], off offset:3840
	v_lshl_add_u64 v[12:13], v[12:13], 0, s[98:99]
	s_waitcnt vmcnt(0)
	v_max_f32_e64 v16, |v16|, |v16|
	v_max_f32_e32 v4, v4, v16
	v_max_f32_e64 v17, |v17|, |v17|
	v_max_f32_e32 v4, v4, v17
	v_max_f32_e64 v18, |v18|, |v18|
	v_max_f32_e32 v4, v4, v18
	v_max_f32_e64 v19, |v19|, |v19|
	v_max_f32_e32 v4, v4, v19
	v_max_f32_e64 v20, |v20|, |v20|
	v_max_f32_e32 v4, v4, v20
	v_max_f32_e64 v21, |v21|, |v21|
	v_max_f32_e32 v4, v4, v21
	v_max_f32_e64 v22, |v22|, |v22|
	v_max_f32_e32 v4, v4, v22
	v_max_f32_e64 v23, |v23|, |v23|
	v_max_f32_e32 v4, v4, v23
	v_max_f32_e64 v24, |v24|, |v24|
	v_max_f32_e32 v4, v4, v24
	v_max_f32_e64 v25, |v25|, |v25|
	v_max_f32_e32 v4, v4, v25
	v_max_f32_e64 v26, |v26|, |v26|
	v_max_f32_e32 v4, v4, v26
	v_max_f32_e64 v27, |v27|, |v27|
	v_max_f32_e32 v4, v4, v27
	v_max_f32_e64 v28, |v28|, |v28|
	v_max_f32_e32 v4, v4, v28
	v_max_f32_e64 v29, |v29|, |v29|
	v_max_f32_e32 v4, v4, v29
	v_max_f32_e64 v30, |v30|, |v30|
	v_max_f32_e32 v4, v4, v30
	v_max_f32_e64 v31, |v31|, |v31|
	v_max_f32_e32 v4, v4, v31
	global_load_dword v16, v[12:13], off
	global_load_dword v17, v[12:13], off offset:256
	global_load_dword v18, v[12:13], off offset:512
	global_load_dword v19, v[12:13], off offset:768
	global_load_dword v20, v[12:13], off offset:1024
	global_load_dword v21, v[12:13], off offset:1280
	global_load_dword v22, v[12:13], off offset:1536
	global_load_dword v23, v[12:13], off offset:1792
	global_load_dword v24, v[12:13], off offset:2048
	global_load_dword v25, v[12:13], off offset:2304
	v_mov_b32_e32 v26, 0
	v_cmp_gt_u32_e32 vcc, 8, v2
	s_and_saveexec_b64 s[6:7], vcc
	global_load_dword v26, v[12:13], off offset:2560
	s_or_b64 exec, exec, s[6:7]
	s_waitcnt vmcnt(0)
	v_max_f32_e64 v16, |v16|, |v16|
	v_max_f32_e32 v4, v4, v16
	v_max_f32_e64 v17, |v17|, |v17|
	v_max_f32_e32 v4, v4, v17
	v_max_f32_e64 v18, |v18|, |v18|
	v_max_f32_e32 v4, v4, v18
	v_max_f32_e64 v19, |v19|, |v19|
	v_max_f32_e32 v4, v4, v19
	v_max_f32_e64 v20, |v20|, |v20|
	v_max_f32_e32 v4, v4, v20
	v_max_f32_e64 v21, |v21|, |v21|
	v_max_f32_e32 v4, v4, v21
	v_max_f32_e64 v22, |v22|, |v22|
	v_max_f32_e32 v4, v4, v22
	v_max_f32_e64 v23, |v23|, |v23|
	v_max_f32_e32 v4, v4, v23
	v_max_f32_e64 v24, |v24|, |v24|
	v_max_f32_e32 v4, v4, v24
	v_max_f32_e64 v25, |v25|, |v25|
	v_max_f32_e32 v4, v4, v25
	v_max_f32_e64 v26, |v26|, |v26|
	v_max_f32_e32 v4, v4, v26

.LBB0_1567:
	s_waitcnt vmcnt(0)
	s_waitcnt lgkmcnt(0)
	s_barrier
	v_readlane_b32 s98, v255, 30
	v_readlane_b32 s99, v255, 31
	s_nop 3
	s_cmp_lg_u64 s[98:99], 0
	s_cbranch_scc1 .Lwo_gsync_do
	v_readlane_b32 s30, v254, 42
	v_readlane_b32 s31, v254, 43
	v_readlane_b32 s42, v254, 44
	v_readlane_b32 s43, v254, 45
	s_mov_b32 s38, 1
	s_mov_b64 s[6:7], 0
	s_branch .LBB0_268
.Lwo_gsync_do:
	s_and_saveexec_b64 s[6:7], s[4:5]
	v_readlane_b32 s42, v254, 44
	v_readlane_b32 s43, v254, 45
	s_cbranch_execz .LBB0_267
	v_readlane_b32 s8, v254, 29
	s_waitcnt vmcnt(0) expcnt(0) lgkmcnt(0)
	s_nop 0
	v_mov_b32_e32 v0, s8
	ds_read_b32 v2, v0
	v_readlane_b32 s8, v254, 30
	s_waitcnt lgkmcnt(0)
	v_cmp_ne_u32_e32 vcc, 0, v2
	v_mov_b32_e32 v0, s8
	ds_read_b32 v0, v0
	s_cbranch_vccnz .LBB0_1583
	s_mov_b32 s14, 1
	s_branch .LBB0_1571

.LBB0_1794:
	s_waitcnt vmcnt(0)
	s_waitcnt vmcnt(0) lgkmcnt(0)
	v_readlane_b32 s98, v254, 51
	v_readlane_b32 s99, v254, 52
	s_nop 3
	s_cmp_lg_u64 s[98:99], 0
	s_cbranch_scc0 .Lnot_last_layer
	s_endpgm
.Lnot_last_layer:
	s_barrier
	s_and_saveexec_b64 s[2:3], s[4:5]
	s_cbranch_execnz .LBB0_1795
	s_getpc_b64 s[98:99]
